# rwkv output pass inner loop hand-scheduled (rows interleaved, single-chain dots, early LDS reads) on top of gdn output/transition pass rewrites and phase-12 rebalancing
# speedup vs baseline: 1.0176x; 1.0085x over previous
; template <int MODE, int RI>
; __device__ __forceinline__ void rwkv_job(const Params& P, float* lw, int head, int seg, int half) {
;     ...
;         for (int s = 0; s < TBK; ++s) {
;             f32x2 w[4], k[4], na[4], b[4], r[4]; float v[8];
;             { const f32x4 x0 = *(const f32x4*)(sw + s * 64 + jg * 8), x1 = *(const f32x4*)(sw + s * 64 + jg * 8 + 4); w[0] = (f32x2){x0.x, x0.y}; w[1] = (f32x2){x0.z, x0.w}; w[2] = (f32x2){x1.x, x1.y}; w[3] = (f32x2){x1.z, x1.w}; }
;             { const f32x4 x0 = *(const f32x4*)(sna + s * 64 + jg * 8), x1 = *(const f32x4*)(sna + s * 64 + jg * 8 + 4); na[0] = (f32x2){x0.x, x0.y}; na[1] = (f32x2){x0.z, x0.w}; na[2] = (f32x2){x1.x, x1.y}; na[3] = (f32x2){x1.z, x1.w}; }
;             { const f32x4 x0 = *(const f32x4*)(sb + s * 64 + jg * 8), x1 = *(const f32x4*)(sb + s * 64 + jg * 8 + 4); b[0] = (f32x2){x0.x, x0.y}; b[1] = (f32x2){x0.z, x0.w}; b[2] = (f32x2){x1.x, x1.y}; b[3] = (f32x2){x1.z, x1.w}; }
;             if (MODE != 0) {
;                 const f32x4 x0 = *(const f32x4*)(sk + s * 64 + jg * 8), x1 = *(const f32x4*)(sk + s * 64 + jg * 8 + 4); k[0] = (f32x2){x0.x, x0.y}; k[1] = (f32x2){x0.z, x0.w}; k[2] = (f32x2){x1.x, x1.y}; k[3] = (f32x2){x1.z, x1.w};
;                 const f32x4 v0 = *(const f32x4*)(sv + s * 64 + row0); v[0] = v0.x; v[1] = v0.y; v[2] = v0.z; v[3] = v0.w;
;                 if (RI == 8) { const f32x4 v1 = *(const f32x4*)(sv + s * 64 + row0 + 4); v[4] = v1.x; v[5] = v1.y; v[6] = v1.z; v[7] = v1.w; }
;             }
;             if (MODE == 2) { const f32x4 x0 = *(const f32x4*)(sr + s * 64 + jg * 8), x1 = *(const f32x4*)(sr + s * 64 + jg * 8 + 4); r[0] = (f32x2){x0.x, x0.y}; r[1] = (f32x2){x0.z, x0.w}; r[2] = (f32x2){x1.x, x1.y}; r[3] = (f32x2){x1.z, x1.w}; }
;             float yk = 0.f;
;             float sa[RI];
; #pragma unroll
;             for (int ri = 0; ri < RI; ++ri) {
;                 f32x2 a2 = S[ri][0] * na[0], a3 = S[ri][1] * na[1];
;                 a2 += S[ri][2] * na[2]; a3 += S[ri][3] * na[3]; a2 += a3;
;                 sa[ri] = a2.x + a2.y;
;             }
; #pragma unroll
;             for (int ri = 0; ri < RI; ++ri) sa[ri] += dppf<0xB1>(sa[ri]);
; #pragma unroll
;             for (int ri = 0; ri < RI; ++ri) sa[ri] += dppf<0x4E>(sa[ri]);
; #pragma unroll
;             for (int ri = 0; ri < RI; ++ri) sa[ri] += dppf<0x141>(sa[ri]);
; #pragma unroll
.LBB0_685:
	v_add_u32_e32 v2, s79, v100
	v_add_u32_e32 v106, s79, v105
	ds_read_b128 v[120:123], v2 offset:10240
	ds_read_b128 v[124:127], v2 offset:10256
	ds_read_b128 v[134:137], v2 offset:12288
	ds_read_b128 v[138:141], v2 offset:12304
	ds_read_b128 v[142:145], v2 offset:6144
	ds_read_b128 v[146:149], v2 offset:6160
	ds_read_b128 v[150:153], v106 offset:2048
	ds_read_b128 v[112:115], v2 offset:4096
	ds_read_b128 v[116:119], v2 offset:4112
	ds_read_b128 v[154:157], v2 offset:2048
	ds_read_b128 v[166:169], v2 offset:2064
	s_waitcnt lgkmcnt(9)
	v_pk_mul_f32 v[220:221], v[58:59], v[120:121]
	v_pk_mul_f32 v[222:223], v[66:67], v[120:121]
	v_pk_mul_f32 v[224:225], v[74:75], v[120:121]
	v_pk_mul_f32 v[226:227], v[82:83], v[120:121]
	v_pk_fma_f32 v[220:221], v[60:61], v[122:123], v[220:221]
	v_pk_fma_f32 v[222:223], v[68:69], v[122:123], v[222:223]
	v_pk_fma_f32 v[224:225], v[76:77], v[122:123], v[224:225]
	v_pk_fma_f32 v[226:227], v[84:85], v[122:123], v[226:227]
	v_pk_fma_f32 v[220:221], v[54:55], v[124:125], v[220:221]
	v_pk_fma_f32 v[222:223], v[62:63], v[124:125], v[222:223]
	v_pk_fma_f32 v[224:225], v[70:71], v[124:125], v[224:225]
	v_pk_fma_f32 v[226:227], v[78:79], v[124:125], v[226:227]
	v_pk_fma_f32 v[220:221], v[56:57], v[126:127], v[220:221]
	v_pk_fma_f32 v[222:223], v[64:65], v[126:127], v[222:223]
	v_pk_fma_f32 v[224:225], v[72:73], v[126:127], v[224:225]
	v_pk_fma_f32 v[226:227], v[80:81], v[126:127], v[226:227]
	v_add_f32_e32 v220, v220, v221
	v_add_f32_e32 v222, v222, v223
	v_add_f32_e32 v224, v224, v225
	v_add_f32_e32 v226, v226, v227
	v_add_f32_dpp v220, v220, v220 quad_perm:[1,0,3,2] row_mask:0xf bank_mask:0xf bound_ctrl:1
	v_add_f32_dpp v222, v222, v222 quad_perm:[1,0,3,2] row_mask:0xf bank_mask:0xf bound_ctrl:1
	v_add_f32_dpp v224, v224, v224 quad_perm:[1,0,3,2] row_mask:0xf bank_mask:0xf bound_ctrl:1
	v_add_f32_dpp v226, v226, v226 quad_perm:[1,0,3,2] row_mask:0xf bank_mask:0xf bound_ctrl:1
	v_add_f32_dpp v220, v220, v220 quad_perm:[2,3,0,1] row_mask:0xf bank_mask:0xf bound_ctrl:1
	v_add_f32_dpp v222, v222, v222 quad_perm:[2,3,0,1] row_mask:0xf bank_mask:0xf bound_ctrl:1
	v_add_f32_dpp v224, v224, v224 quad_perm:[2,3,0,1] row_mask:0xf bank_mask:0xf bound_ctrl:1
	v_add_f32_dpp v226, v226, v226 quad_perm:[2,3,0,1] row_mask:0xf bank_mask:0xf bound_ctrl:1
	v_add_f32_dpp v220, v220, v220 row_half_mirror row_mask:0xf bank_mask:0xf bound_ctrl:1
	v_add_f32_dpp v222, v222, v222 row_half_mirror row_mask:0xf bank_mask:0xf bound_ctrl:1
	v_add_f32_dpp v224, v224, v224 row_half_mirror row_mask:0xf bank_mask:0xf bound_ctrl:1
	v_add_f32_dpp v226, v226, v226 row_half_mirror row_mask:0xf bank_mask:0xf bound_ctrl:1
	s_waitcnt lgkmcnt(2)
	v_pk_mul_f32 v[228:229], v[134:135], v[220:221] op_sel_hi:[1,0]
	v_pk_mul_f32 v[230:231], v[134:135], v[222:223] op_sel_hi:[1,0]
	v_pk_mul_f32 v[232:233], v[134:135], v[224:225] op_sel_hi:[1,0]
	v_pk_mul_f32 v[234:235], v[134:135], v[226:227] op_sel_hi:[1,0]
	v_pk_fma_f32 v[228:229], v[142:143], v[150:151], v[228:229] op_sel_hi:[1,0,1]
	v_pk_fma_f32 v[230:231], v[142:143], v[150:151], v[230:231] op_sel:[0,1,0]
	v_pk_fma_f32 v[232:233], v[142:143], v[152:153], v[232:233] op_sel_hi:[1,0,1]
	v_pk_fma_f32 v[234:235], v[142:143], v[152:153], v[234:235] op_sel:[0,1,0]
	v_pk_fma_f32 v[58:59], v[58:59], v[112:113], v[228:229]
	v_pk_fma_f32 v[66:67], v[66:67], v[112:113], v[230:231]
	v_pk_fma_f32 v[74:75], v[74:75], v[112:113], v[232:233]
	v_pk_fma_f32 v[82:83], v[82:83], v[112:113], v[234:235]
	v_pk_mul_f32 v[228:229], v[136:137], v[220:221] op_sel_hi:[1,0]
	v_pk_mul_f32 v[230:231], v[136:137], v[222:223] op_sel_hi:[1,0]
	v_pk_mul_f32 v[232:233], v[136:137], v[224:225] op_sel_hi:[1,0]
	v_pk_mul_f32 v[234:235], v[136:137], v[226:227] op_sel_hi:[1,0]
	v_pk_fma_f32 v[228:229], v[144:145], v[150:151], v[228:229] op_sel_hi:[1,0,1]
	v_pk_fma_f32 v[230:231], v[144:145], v[150:151], v[230:231] op_sel:[0,1,0]
	v_pk_fma_f32 v[232:233], v[144:145], v[152:153], v[232:233] op_sel_hi:[1,0,1]
	v_pk_fma_f32 v[234:235], v[144:145], v[152:153], v[234:235] op_sel:[0,1,0]
	v_pk_fma_f32 v[60:61], v[60:61], v[114:115], v[228:229]
	v_pk_fma_f32 v[68:69], v[68:69], v[114:115], v[230:231]
	v_pk_fma_f32 v[76:77], v[76:77], v[114:115], v[232:233]
	v_pk_fma_f32 v[84:85], v[84:85], v[114:115], v[234:235]
	v_pk_mul_f32 v[228:229], v[138:139], v[220:221] op_sel_hi:[1,0]
	v_pk_mul_f32 v[230:231], v[138:139], v[222:223] op_sel_hi:[1,0]
	v_pk_mul_f32 v[232:233], v[138:139], v[224:225] op_sel_hi:[1,0]
	v_pk_mul_f32 v[234:235], v[138:139], v[226:227] op_sel_hi:[1,0]
	v_pk_fma_f32 v[228:229], v[146:147], v[150:151], v[228:229] op_sel_hi:[1,0,1]
	v_pk_fma_f32 v[230:231], v[146:147], v[150:151], v[230:231] op_sel:[0,1,0]
	v_pk_fma_f32 v[232:233], v[146:147], v[152:153], v[232:233] op_sel_hi:[1,0,1]
	v_pk_fma_f32 v[234:235], v[146:147], v[152:153], v[234:235] op_sel:[0,1,0]
	v_pk_fma_f32 v[54:55], v[54:55], v[116:117], v[228:229]
	v_pk_fma_f32 v[62:63], v[62:63], v[116:117], v[230:231]
	v_pk_fma_f32 v[70:71], v[70:71], v[116:117], v[232:233]
	v_pk_fma_f32 v[78:79], v[78:79], v[116:117], v[234:235]
	v_pk_mul_f32 v[228:229], v[140:141], v[220:221] op_sel_hi:[1,0]
	v_pk_mul_f32 v[230:231], v[140:141], v[222:223] op_sel_hi:[1,0]
	v_pk_mul_f32 v[232:233], v[140:141], v[224:225] op_sel_hi:[1,0]
	v_pk_mul_f32 v[234:235], v[140:141], v[226:227] op_sel_hi:[1,0]
	v_pk_fma_f32 v[228:229], v[148:149], v[150:151], v[228:229] op_sel_hi:[1,0,1]
	v_pk_fma_f32 v[230:231], v[148:149], v[150:151], v[230:231] op_sel:[0,1,0]
	v_pk_fma_f32 v[232:233], v[148:149], v[152:153], v[232:233] op_sel_hi:[1,0,1]
	v_pk_fma_f32 v[234:235], v[148:149], v[152:153], v[234:235] op_sel:[0,1,0]
	v_pk_fma_f32 v[56:57], v[56:57], v[118:119], v[228:229]
	v_pk_fma_f32 v[64:65], v[64:65], v[118:119], v[230:231]
	v_pk_fma_f32 v[72:73], v[72:73], v[118:119], v[232:233]
	v_pk_fma_f32 v[80:81], v[80:81], v[118:119], v[234:235]
	ds_read_b128 v[120:123], v2 offset:10496
	ds_read_b128 v[124:127], v2 offset:10512
	ds_read_b128 v[134:137], v2 offset:12544
	ds_read_b128 v[138:141], v2 offset:12560
	ds_read_b128 v[142:145], v2 offset:6400
	ds_read_b128 v[146:149], v2 offset:6416
	ds_read_b128 v[150:153], v106 offset:2304
	ds_read_b128 v[112:115], v2 offset:4352
	ds_read_b128 v[116:119], v2 offset:4368
	s_waitcnt lgkmcnt(9)
; __device__ __forceinline__ bf16_t f2bf(float f) { return (bf16_t)(cvt_pk_bf16(f, 0.f) & 0xffffu); }
; template <int CTRL> __device__ __forceinline__ float dppf(float v) { return __builtin_bit_cast(float, __builtin_amdgcn_update_dpp(0, __builtin_bit_cast(int, v), CTRL, 0xF, 0xF, true)); }
; template <int MODE, int RI>
; __device__ __forceinline__ void rwkv_job(const Params& P, float* lw, int head, int seg, int half) {
;     ...
;             for (int ri = 0; ri < RI; ++ri) {
;                 f32x2 a2 = S[ri][0] * na[0], a3 = S[ri][1] * na[1];
;                 a2 += S[ri][2] * na[2]; a3 += S[ri][3] * na[3]; a2 += a3;
;                 sa[ri] = a2.x + a2.y;
;             }
; #pragma unroll
;             for (int ri = 0; ri < RI; ++ri) sa[ri] += dppf<0xB1>(sa[ri]);
; #pragma unroll
;             for (int ri = 0; ri < RI; ++ri) sa[ri] += dppf<0x4E>(sa[ri]);
; #pragma unroll
;             for (int ri = 0; ri < RI; ++ri) sa[ri] += dppf<0x141>(sa[ri]);
; #pragma unroll
;             for (int ri = 0; ri < RI; ++ri) {
; #pragma unroll
;                 for (int jj = 0; jj < 4; ++jj) { f32x2 tmp = b[jj] * sa[ri]; if (MODE != 0) tmp += k[jj] * v[ri]; S[ri][jj] = S[ri][jj] * w[jj] + tmp; }
;             }
;             if (MODE == 2) {
;                 float ys[RI];
; #pragma unroll
;                 for (int ri = 0; ri < RI; ++ri) {
;                     f32x2 y2 = S[ri][0] * r[0], y3 = S[ri][1] * r[1];
;                     y2 += S[ri][2] * r[2]; y3 += S[ri][3] * r[3]; y2 += y3;
;                     ys[ri] = y2.x + y2.y;
;                 }
; #pragma unroll
;                 for (int ri = 0; ri < RI; ++ri) ys[ri] += dppf<0xB1>(ys[ri]);
; #pragma unroll
;                 for (int ri = 0; ri < RI; ++ri) ys[ri] += dppf<0x4E>(ys[ri]);
; #pragma unroll
;                 for (int ri = 0; ri < RI; ++ri) ys[ri] += dppf<0x141>(ys[ri]);
; #pragma unroll
;                 for (int ri = 0; ri < RI; ++ri) yk = (jg == ri) ? ys[ri] : yk;
;             }
;             if (MODE == 2) { if (RI == 8 || jg < 4) proj[(size_t)(tbase + blk * TBK + s) * PLD + PC_K + head * 64 + row0 + jg] = f2bf(yk); }
	v_pk_mul_f32 v[220:221], v[58:59], v[154:155]
	v_pk_mul_f32 v[222:223], v[66:67], v[154:155]
	v_pk_mul_f32 v[224:225], v[74:75], v[154:155]
	v_pk_mul_f32 v[226:227], v[82:83], v[154:155]
	v_pk_fma_f32 v[220:221], v[60:61], v[156:157], v[220:221]
	v_pk_fma_f32 v[222:223], v[68:69], v[156:157], v[222:223]
	v_pk_fma_f32 v[224:225], v[76:77], v[156:157], v[224:225]
	v_pk_fma_f32 v[226:227], v[84:85], v[156:157], v[226:227]
	v_pk_fma_f32 v[220:221], v[54:55], v[166:167], v[220:221]
	v_pk_fma_f32 v[222:223], v[62:63], v[166:167], v[222:223]
	v_pk_fma_f32 v[224:225], v[70:71], v[166:167], v[224:225]
	v_pk_fma_f32 v[226:227], v[78:79], v[166:167], v[226:227]
	v_pk_fma_f32 v[220:221], v[56:57], v[168:169], v[220:221]
	v_pk_fma_f32 v[222:223], v[64:65], v[168:169], v[222:223]
	v_pk_fma_f32 v[224:225], v[72:73], v[168:169], v[224:225]
	v_pk_fma_f32 v[226:227], v[80:81], v[168:169], v[226:227]
	v_add_f32_e32 v220, v220, v221
	v_add_f32_e32 v222, v222, v223
	v_add_f32_e32 v224, v224, v225
	v_add_f32_e32 v226, v226, v227
	v_add_f32_dpp v220, v220, v220 quad_perm:[1,0,3,2] row_mask:0xf bank_mask:0xf bound_ctrl:1
	v_add_f32_dpp v222, v222, v222 quad_perm:[1,0,3,2] row_mask:0xf bank_mask:0xf bound_ctrl:1
	v_add_f32_dpp v224, v224, v224 quad_perm:[1,0,3,2] row_mask:0xf bank_mask:0xf bound_ctrl:1
	v_add_f32_dpp v226, v226, v226 quad_perm:[1,0,3,2] row_mask:0xf bank_mask:0xf bound_ctrl:1
	v_add_f32_dpp v220, v220, v220 quad_perm:[2,3,0,1] row_mask:0xf bank_mask:0xf bound_ctrl:1
	v_add_f32_dpp v222, v222, v222 quad_perm:[2,3,0,1] row_mask:0xf bank_mask:0xf bound_ctrl:1
	v_add_f32_dpp v224, v224, v224 quad_perm:[2,3,0,1] row_mask:0xf bank_mask:0xf bound_ctrl:1
	v_add_f32_dpp v226, v226, v226 quad_perm:[2,3,0,1] row_mask:0xf bank_mask:0xf bound_ctrl:1
	v_add_f32_dpp v220, v220, v220 row_half_mirror row_mask:0xf bank_mask:0xf bound_ctrl:1
	v_add_f32_dpp v222, v222, v222 row_half_mirror row_mask:0xf bank_mask:0xf bound_ctrl:1
	v_add_f32_dpp v224, v224, v224 row_half_mirror row_mask:0xf bank_mask:0xf bound_ctrl:1
	v_add_f32_dpp v226, v226, v226 row_half_mirror row_mask:0xf bank_mask:0xf bound_ctrl:1
	ds_read_b128 v[154:157], v2 offset:2304
	ds_read_b128 v[166:169], v2 offset:2320
	s_and_saveexec_b64 s[18:19], s[8:9]
	v_cndmask_b32_e64 v220, 0, v220, s[10:11]
	v_cndmask_b32_e64 v220, v220, v222, s[12:13]
	v_cndmask_b32_e64 v220, v220, v224, s[14:15]
	v_cndmask_b32_e64 v220, v220, v226, s[16:17]
	v_add_co_u32_e32 v236, vcc, 0xffffd000, v98
	v_cvt_pk_bf16_f32 v220, v220, s0
	s_nop 0
	v_addc_co_u32_e32 v237, vcc, -1, v99, vcc
	global_store_short v[236:237], v220, off offset:-1024
	s_or_b64 exec, exec, s[18:19]
	s_waitcnt lgkmcnt(9)
	v_pk_mul_f32 v[220:221], v[58:59], v[120:121]
	v_pk_mul_f32 v[222:223], v[66:67], v[120:121]
	v_pk_mul_f32 v[224:225], v[74:75], v[120:121]
	v_pk_mul_f32 v[226:227], v[82:83], v[120:121]
	v_pk_fma_f32 v[220:221], v[60:61], v[122:123], v[220:221]
	v_pk_fma_f32 v[222:223], v[68:69], v[122:123], v[222:223]
	v_pk_fma_f32 v[224:225], v[76:77], v[122:123], v[224:225]
	v_pk_fma_f32 v[226:227], v[84:85], v[122:123], v[226:227]
	v_pk_fma_f32 v[220:221], v[54:55], v[124:125], v[220:221]
	v_pk_fma_f32 v[222:223], v[62:63], v[124:125], v[222:223]
	v_pk_fma_f32 v[224:225], v[70:71], v[124:125], v[224:225]
	v_pk_fma_f32 v[226:227], v[78:79], v[124:125], v[226:227]
	v_pk_fma_f32 v[220:221], v[56:57], v[126:127], v[220:221]
	v_pk_fma_f32 v[222:223], v[64:65], v[126:127], v[222:223]
	v_pk_fma_f32 v[224:225], v[72:73], v[126:127], v[224:225]
	v_pk_fma_f32 v[226:227], v[80:81], v[126:127], v[226:227]
	v_add_f32_e32 v220, v220, v221
	v_add_f32_e32 v222, v222, v223
	v_add_f32_e32 v224, v224, v225
	v_add_f32_e32 v226, v226, v227
	v_add_f32_dpp v220, v220, v220 quad_perm:[1,0,3,2] row_mask:0xf bank_mask:0xf bound_ctrl:1
	v_add_f32_dpp v222, v222, v222 quad_perm:[1,0,3,2] row_mask:0xf bank_mask:0xf bound_ctrl:1
	v_add_f32_dpp v224, v224, v224 quad_perm:[1,0,3,2] row_mask:0xf bank_mask:0xf bound_ctrl:1
	v_add_f32_dpp v226, v226, v226 quad_perm:[1,0,3,2] row_mask:0xf bank_mask:0xf bound_ctrl:1
	v_add_f32_dpp v220, v220, v220 quad_perm:[2,3,0,1] row_mask:0xf bank_mask:0xf bound_ctrl:1
	v_add_f32_dpp v222, v222, v222 quad_perm:[2,3,0,1] row_mask:0xf bank_mask:0xf bound_ctrl:1
	v_add_f32_dpp v224, v224, v224 quad_perm:[2,3,0,1] row_mask:0xf bank_mask:0xf bound_ctrl:1
	v_add_f32_dpp v226, v226, v226 quad_perm:[2,3,0,1] row_mask:0xf bank_mask:0xf bound_ctrl:1
	v_add_f32_dpp v220, v220, v220 row_half_mirror row_mask:0xf bank_mask:0xf bound_ctrl:1
	v_add_f32_dpp v222, v222, v222 row_half_mirror row_mask:0xf bank_mask:0xf bound_ctrl:1
	v_add_f32_dpp v224, v224, v224 row_half_mirror row_mask:0xf bank_mask:0xf bound_ctrl:1
	v_add_f32_dpp v226, v226, v226 row_half_mirror row_mask:0xf bank_mask:0xf bound_ctrl:1
	s_waitcnt lgkmcnt(2)
; __device__ __forceinline__ bf16_t f2bf(float f) { return (bf16_t)(cvt_pk_bf16(f, 0.f) & 0xffffu); }
; template <int CTRL> __device__ __forceinline__ float dppf(float v) { return __builtin_bit_cast(float, __builtin_amdgcn_update_dpp(0, __builtin_bit_cast(int, v), CTRL, 0xF, 0xF, true)); }
; template <int MODE, int RI>
; __device__ __forceinline__ void rwkv_job(const Params& P, float* lw, int head, int seg, int half) {
;     ...
;             for (int ri = 0; ri < RI; ++ri) {
; #pragma unroll
;                 for (int jj = 0; jj < 4; ++jj) { f32x2 tmp = b[jj] * sa[ri]; if (MODE != 0) tmp += k[jj] * v[ri]; S[ri][jj] = S[ri][jj] * w[jj] + tmp; }
;             }
;             if (MODE == 2) {
;                 float ys[RI];
; #pragma unroll
;                 for (int ri = 0; ri < RI; ++ri) {
;                     f32x2 y2 = S[ri][0] * r[0], y3 = S[ri][1] * r[1];
;                     y2 += S[ri][2] * r[2]; y3 += S[ri][3] * r[3]; y2 += y3;
;                     ys[ri] = y2.x + y2.y;
;                 }
; #pragma unroll
;                 for (int ri = 0; ri < RI; ++ri) ys[ri] += dppf<0xB1>(ys[ri]);
; #pragma unroll
;                 for (int ri = 0; ri < RI; ++ri) ys[ri] += dppf<0x4E>(ys[ri]);
; #pragma unroll
;                 for (int ri = 0; ri < RI; ++ri) ys[ri] += dppf<0x141>(ys[ri]);
; #pragma unroll
;                 for (int ri = 0; ri < RI; ++ri) yk = (jg == ri) ? ys[ri] : yk;
;             }
;             if (MODE == 2) { if (RI == 8 || jg < 4) proj[(size_t)(tbase + blk * TBK + s) * PLD + PC_K + head * 64 + row0 + jg] = f2bf(yk); }
	v_pk_mul_f32 v[228:229], v[134:135], v[220:221] op_sel_hi:[1,0]
	v_pk_mul_f32 v[230:231], v[134:135], v[222:223] op_sel_hi:[1,0]
	v_pk_mul_f32 v[232:233], v[134:135], v[224:225] op_sel_hi:[1,0]
	v_pk_mul_f32 v[234:235], v[134:135], v[226:227] op_sel_hi:[1,0]
	v_pk_fma_f32 v[228:229], v[142:143], v[150:151], v[228:229] op_sel_hi:[1,0,1]
	v_pk_fma_f32 v[230:231], v[142:143], v[150:151], v[230:231] op_sel:[0,1,0]
	v_pk_fma_f32 v[232:233], v[142:143], v[152:153], v[232:233] op_sel_hi:[1,0,1]
	v_pk_fma_f32 v[234:235], v[142:143], v[152:153], v[234:235] op_sel:[0,1,0]
	v_pk_fma_f32 v[58:59], v[58:59], v[112:113], v[228:229]
	v_pk_fma_f32 v[66:67], v[66:67], v[112:113], v[230:231]
	v_pk_fma_f32 v[74:75], v[74:75], v[112:113], v[232:233]
	v_pk_fma_f32 v[82:83], v[82:83], v[112:113], v[234:235]
	v_pk_mul_f32 v[228:229], v[136:137], v[220:221] op_sel_hi:[1,0]
	v_pk_mul_f32 v[230:231], v[136:137], v[222:223] op_sel_hi:[1,0]
	v_pk_mul_f32 v[232:233], v[136:137], v[224:225] op_sel_hi:[1,0]
	v_pk_mul_f32 v[234:235], v[136:137], v[226:227] op_sel_hi:[1,0]
	v_pk_fma_f32 v[228:229], v[144:145], v[150:151], v[228:229] op_sel_hi:[1,0,1]
	v_pk_fma_f32 v[230:231], v[144:145], v[150:151], v[230:231] op_sel:[0,1,0]
	v_pk_fma_f32 v[232:233], v[144:145], v[152:153], v[232:233] op_sel_hi:[1,0,1]
	v_pk_fma_f32 v[234:235], v[144:145], v[152:153], v[234:235] op_sel:[0,1,0]
	v_pk_fma_f32 v[60:61], v[60:61], v[114:115], v[228:229]
	v_pk_fma_f32 v[68:69], v[68:69], v[114:115], v[230:231]
	v_pk_fma_f32 v[76:77], v[76:77], v[114:115], v[232:233]
	v_pk_fma_f32 v[84:85], v[84:85], v[114:115], v[234:235]
	v_pk_mul_f32 v[228:229], v[138:139], v[220:221] op_sel_hi:[1,0]
	v_pk_mul_f32 v[230:231], v[138:139], v[222:223] op_sel_hi:[1,0]
	v_pk_mul_f32 v[232:233], v[138:139], v[224:225] op_sel_hi:[1,0]
	v_pk_mul_f32 v[234:235], v[138:139], v[226:227] op_sel_hi:[1,0]
	v_pk_fma_f32 v[228:229], v[146:147], v[150:151], v[228:229] op_sel_hi:[1,0,1]
	v_pk_fma_f32 v[230:231], v[146:147], v[150:151], v[230:231] op_sel:[0,1,0]
	v_pk_fma_f32 v[232:233], v[146:147], v[152:153], v[232:233] op_sel_hi:[1,0,1]
	v_pk_fma_f32 v[234:235], v[146:147], v[152:153], v[234:235] op_sel:[0,1,0]
	v_pk_fma_f32 v[54:55], v[54:55], v[116:117], v[228:229]
	v_pk_fma_f32 v[62:63], v[62:63], v[116:117], v[230:231]
	v_pk_fma_f32 v[70:71], v[70:71], v[116:117], v[232:233]
	v_pk_fma_f32 v[78:79], v[78:79], v[116:117], v[234:235]
	v_pk_mul_f32 v[228:229], v[140:141], v[220:221] op_sel_hi:[1,0]
	v_pk_mul_f32 v[230:231], v[140:141], v[222:223] op_sel_hi:[1,0]
	v_pk_mul_f32 v[232:233], v[140:141], v[224:225] op_sel_hi:[1,0]
	v_pk_mul_f32 v[234:235], v[140:141], v[226:227] op_sel_hi:[1,0]
	v_pk_fma_f32 v[228:229], v[148:149], v[150:151], v[228:229] op_sel_hi:[1,0,1]
	v_pk_fma_f32 v[230:231], v[148:149], v[150:151], v[230:231] op_sel:[0,1,0]
	v_pk_fma_f32 v[232:233], v[148:149], v[152:153], v[232:233] op_sel_hi:[1,0,1]
	v_pk_fma_f32 v[234:235], v[148:149], v[152:153], v[234:235] op_sel:[0,1,0]
	v_pk_fma_f32 v[56:57], v[56:57], v[118:119], v[228:229]
	v_pk_fma_f32 v[64:65], v[64:65], v[118:119], v[230:231]
	v_pk_fma_f32 v[72:73], v[72:73], v[118:119], v[232:233]
	v_pk_fma_f32 v[80:81], v[80:81], v[118:119], v[234:235]
	s_waitcnt lgkmcnt(0)
	v_pk_mul_f32 v[220:221], v[58:59], v[154:155]
	v_pk_mul_f32 v[222:223], v[66:67], v[154:155]
	v_pk_mul_f32 v[224:225], v[74:75], v[154:155]
	v_pk_mul_f32 v[226:227], v[82:83], v[154:155]
	v_pk_fma_f32 v[220:221], v[60:61], v[156:157], v[220:221]
	v_pk_fma_f32 v[222:223], v[68:69], v[156:157], v[222:223]
	v_pk_fma_f32 v[224:225], v[76:77], v[156:157], v[224:225]
	v_pk_fma_f32 v[226:227], v[84:85], v[156:157], v[226:227]
	v_pk_fma_f32 v[220:221], v[54:55], v[166:167], v[220:221]
	v_pk_fma_f32 v[222:223], v[62:63], v[166:167], v[222:223]
	v_pk_fma_f32 v[224:225], v[70:71], v[166:167], v[224:225]
	v_pk_fma_f32 v[226:227], v[78:79], v[166:167], v[226:227]
	v_pk_fma_f32 v[220:221], v[56:57], v[168:169], v[220:221]
	v_pk_fma_f32 v[222:223], v[64:65], v[168:169], v[222:223]
	v_pk_fma_f32 v[224:225], v[72:73], v[168:169], v[224:225]
	v_pk_fma_f32 v[226:227], v[80:81], v[168:169], v[226:227]
	v_add_f32_e32 v220, v220, v221
	v_add_f32_e32 v222, v222, v223
	v_add_f32_e32 v224, v224, v225
	v_add_f32_e32 v226, v226, v227
	v_add_f32_dpp v220, v220, v220 quad_perm:[1,0,3,2] row_mask:0xf bank_mask:0xf bound_ctrl:1
	v_add_f32_dpp v222, v222, v222 quad_perm:[1,0,3,2] row_mask:0xf bank_mask:0xf bound_ctrl:1
	v_add_f32_dpp v224, v224, v224 quad_perm:[1,0,3,2] row_mask:0xf bank_mask:0xf bound_ctrl:1
	v_add_f32_dpp v226, v226, v226 quad_perm:[1,0,3,2] row_mask:0xf bank_mask:0xf bound_ctrl:1
	v_add_f32_dpp v220, v220, v220 quad_perm:[2,3,0,1] row_mask:0xf bank_mask:0xf bound_ctrl:1
	v_add_f32_dpp v222, v222, v222 quad_perm:[2,3,0,1] row_mask:0xf bank_mask:0xf bound_ctrl:1
	v_add_f32_dpp v224, v224, v224 quad_perm:[2,3,0,1] row_mask:0xf bank_mask:0xf bound_ctrl:1
	v_add_f32_dpp v226, v226, v226 quad_perm:[2,3,0,1] row_mask:0xf bank_mask:0xf bound_ctrl:1
	v_add_f32_dpp v220, v220, v220 row_half_mirror row_mask:0xf bank_mask:0xf bound_ctrl:1
	v_add_f32_dpp v222, v222, v222 row_half_mirror row_mask:0xf bank_mask:0xf bound_ctrl:1
	v_add_f32_dpp v224, v224, v224 row_half_mirror row_mask:0xf bank_mask:0xf bound_ctrl:1
	v_add_f32_dpp v226, v226, v226 row_half_mirror row_mask:0xf bank_mask:0xf bound_ctrl:1
	s_and_saveexec_b64 s[18:19], s[8:9]
	v_cndmask_b32_e64 v220, 0, v220, s[10:11]
	v_cndmask_b32_e64 v220, v220, v222, s[12:13]
	v_cndmask_b32_e64 v220, v220, v224, s[14:15]
	v_cndmask_b32_e64 v220, v220, v226, s[16:17]
	v_cvt_pk_bf16_f32 v220, v220, s0
	s_nop 0
	global_store_short v[98:99], v220, off
	s_or_b64 exec, exec, s[18:19]
	s_branch .LBB0_684
